# all de-serialisation hoists kept; GEMM K-loop runs with no priority changes at all (template toggles and the static raise both removed)
# baseline (speedup 1.0000x reference)
; #define PG8_STAGE(bufoff, gbase, voff) do { _Pragma("unroll") for (int _i = 0; _i < 2; ++_i) \
;         __builtin_amdgcn_global_load_lds((const unsigned*)((const char*)(gbase) + (voff)[_i]), (PG8_LAS unsigned*)(lds + (bufoff) + ldsw + _i * 8192), 16, 0, 0); } while (0)
; #define PG8_LDA(dst, b, h) do { _Pragma("unroll") for (int m = 0; m < 4; ++m) _Pragma("unroll") for (int k = 0; k < 2; ++k) dst[m][k] = *(const PG8_LAS bf16x8*)(lds + PG8_SA(b, h) + aoff + m * 2048 + k * 1024); } while (0)
; #define PG8_LDB(dst, b, h) do { _Pragma("unroll") for (int n = 0; n < 2; ++n) _Pragma("unroll") for (int k = 0; k < 2; ++k) dst[n][k] = *(const PG8_LAS bf16x8*)(lds + PG8_SB(b, h) + boff + n * 2048 + k * 1024); } while (0)
; #define PG8_MMA(ai, bj, At, Bt) do { __builtin_amdgcn_s_setprio(1); _Pragma("unroll") for (int m = 0; m < 4; ++m) _Pragma("unroll") for (int n = 0; n < 2; ++n) _Pragma("unroll") for (int k = 0; k < 2; ++k) \
;         acc[ai][bj][m][n] = __builtin_amdgcn_mfma_f32_16x16x32_bf16(Bt[n][k], At[m][k], acc[ai][bj][m][n], 0, 0, 0); __builtin_amdgcn_s_setprio(0); } while (0)
; #define PG8_WAIT_V(n) asm volatile("s_waitcnt vmcnt(" #n ")" ::: "memory")
; #define PG8_WAIT_L(n) asm volatile("s_waitcnt lgkmcnt(" #n ")" ::: "memory")
; #define PG8_BAR __builtin_amdgcn_s_barrier()
; #define PG8_SCHED __builtin_amdgcn_sched_barrier(0)
; template <class Epi, class Sched, bool ALIGN_EPI = false, bool SP2 = false>
; __device__ __forceinline__ void gemm_phase(PG8_LAS unsigned char* lds, const Gemm g, const Sched& S, const Epi& E) {
;     ...
;             PG8_LDB(B0, 0, 0); PG8_LDB(B1, 0, 1); PG8_SCHED; PG8_LDA(At, 0, 0); PG8_STAGE(PG8_SA(1, 1), a1 + hstep, voffA);
;             PG8_WAIT_V(8); PG8_WAIT_L(0); PG8_BAR; PG8_MMA(0, 0, At, B0); PG8_MMA(0, 1, At, B1); PG8_BAR; PG8_SCHED;
;     ...
; #pragma unroll
;         for (int a = 0; a < 2; ++a)
; #pragma unroll
;             for (int b = 0; b < 2; ++b)
; #pragma unroll
;                 for (int m = 0; m < 4; ++m)
; #pragma unroll
;                     for (int n = 0; n < 2; ++n) acc[a][b][m][n] = (f32x4){0.f, 0.f, 0.f, 0.f};
;         cur = nxt; cA = nA; cB = nB; ++ui;
.LBB0_185:
	s_add_u32 s12, s12, 0x80
	s_addc_u32 s13, s13, 0
	s_add_u32 s16, s14, 0x100
	v_mov_b32_e32 v0, 0
	s_addc_u32 s17, s15, 0
	s_mov_b32 s0, 0
	v_mov_b32_e32 v1, v0
	v_mov_b32_e32 v2, v0
	v_mov_b32_e32 v3, v0
	v_mov_b32_e32 v4, v0
	v_mov_b32_e32 v5, v0
	v_mov_b32_e32 v6, v0
	v_mov_b32_e32 v7, v0
	v_mov_b32_e32 v8, v0
	v_mov_b32_e32 v9, v0
	v_mov_b32_e32 v10, v0
	v_mov_b32_e32 v11, v0
	v_mov_b32_e32 v16, v0
	v_mov_b32_e32 v17, v0
	v_mov_b32_e32 v18, v0
	v_mov_b32_e32 v19, v0
	v_mov_b32_e32 v24, v0
	v_mov_b32_e32 v25, v0
	v_mov_b32_e32 v26, v0
	v_mov_b32_e32 v27, v0
	v_mov_b32_e32 v32, v0
	v_mov_b32_e32 v33, v0
	v_mov_b32_e32 v34, v0
	v_mov_b32_e32 v35, v0
	v_mov_b32_e32 v40, v0
	v_mov_b32_e32 v41, v0
	v_mov_b32_e32 v42, v0
	v_mov_b32_e32 v43, v0
	v_mov_b32_e32 v48, v0
	v_mov_b32_e32 v49, v0
	v_mov_b32_e32 v50, v0
	v_mov_b32_e32 v51, v0
	v_mov_b32_e32 v12, v0
	v_mov_b32_e32 v13, v0
	v_mov_b32_e32 v14, v0
	v_mov_b32_e32 v15, v0
	v_mov_b32_e32 v20, v0
	v_mov_b32_e32 v21, v0
	v_mov_b32_e32 v22, v0
	v_mov_b32_e32 v23, v0
	v_mov_b32_e32 v28, v0
	v_mov_b32_e32 v29, v0
	v_mov_b32_e32 v30, v0
	v_mov_b32_e32 v31, v0
	v_mov_b32_e32 v36, v0
	v_mov_b32_e32 v37, v0
	v_mov_b32_e32 v38, v0
	v_mov_b32_e32 v39, v0
	v_mov_b32_e32 v44, v0
	v_mov_b32_e32 v45, v0
	v_mov_b32_e32 v46, v0
	v_mov_b32_e32 v47, v0
	v_mov_b32_e32 v52, v0
	v_mov_b32_e32 v53, v0
	v_mov_b32_e32 v54, v0
	v_mov_b32_e32 v55, v0
	v_mov_b32_e32 v56, v0
	v_mov_b32_e32 v57, v0
	v_mov_b32_e32 v58, v0
	v_mov_b32_e32 v59, v0
	v_mov_b32_e32 v60, v0
	v_mov_b32_e32 v61, v0
	v_mov_b32_e32 v62, v0
	v_mov_b32_e32 v63, v0
	v_mov_b32_e32 v64, v0
	v_mov_b32_e32 v65, v0
	v_mov_b32_e32 v66, v0
	v_mov_b32_e32 v67, v0
	v_mov_b32_e32 v68, v0
	v_mov_b32_e32 v69, v0
	v_mov_b32_e32 v70, v0
	v_mov_b32_e32 v71, v0
	v_mov_b32_e32 v72, v0
	v_mov_b32_e32 v73, v0
	v_mov_b32_e32 v74, v0
	v_mov_b32_e32 v75, v0
	v_mov_b32_e32 v76, v0
	v_mov_b32_e32 v77, v0
	v_mov_b32_e32 v78, v0
	v_mov_b32_e32 v79, v0
	v_mov_b32_e32 v88, v0
	v_mov_b32_e32 v89, v0
	v_mov_b32_e32 v90, v0
	v_mov_b32_e32 v91, v0
	v_mov_b32_e32 v92, v0
	v_mov_b32_e32 v93, v0
	v_mov_b32_e32 v94, v0
	v_mov_b32_e32 v95, v0
	v_mov_b32_e32 v104, v0
	v_mov_b32_e32 v105, v0
	v_mov_b32_e32 v106, v0
	v_mov_b32_e32 v107, v0
	v_mov_b32_e32 v108, v0
	v_mov_b32_e32 v109, v0
	v_mov_b32_e32 v110, v0
	v_mov_b32_e32 v111, v0
	v_mov_b32_e32 v80, v0
	v_mov_b32_e32 v81, v0
	v_mov_b32_e32 v82, v0
	v_mov_b32_e32 v83, v0
	v_mov_b32_e32 v84, v0
	v_mov_b32_e32 v85, v0
	v_mov_b32_e32 v86, v0
	v_mov_b32_e32 v87, v0
	v_mov_b32_e32 v96, v0
	v_mov_b32_e32 v97, v0
	v_mov_b32_e32 v98, v0
	v_mov_b32_e32 v99, v0
	v_mov_b32_e32 v100, v0
	v_mov_b32_e32 v101, v0
	v_mov_b32_e32 v102, v0
	v_mov_b32_e32 v103, v0
	v_mov_b32_e32 v112, v0
	v_mov_b32_e32 v113, v0
	v_mov_b32_e32 v114, v0
	v_mov_b32_e32 v115, v0
	v_mov_b32_e32 v116, v0
	v_mov_b32_e32 v117, v0
	v_mov_b32_e32 v118, v0
	v_mov_b32_e32 v119, v0
	v_mov_b32_e32 v120, v0
	v_mov_b32_e32 v121, v0
	v_mov_b32_e32 v122, v0
	v_mov_b32_e32 v123, v0
	v_mov_b32_e32 v124, v0
	v_mov_b32_e32 v125, v0
	v_mov_b32_e32 v126, v0
	v_mov_b32_e32 v127, v0
.LBB0_186:
	s_add_i32 s1, s0, 2
	s_add_u32 s2, s12, 0x80
	s_addc_u32 s3, s13, 0
	s_add_i32 s33, 0, 0x10000
	s_cmp_eq_u32 s29, s0
	s_cselect_b32 s15, s73, s3
	s_cselect_b32 s14, s72, s2
	s_cselect_b32 s3, s5, s17
	s_cselect_b32 s2, s4, s16
	s_add_i32 s0, 0, 0x14000
	v_add_u32_e32 v140, s33, v252
	v_add_u32_e32 v156, s0, v252
	s_waitcnt lgkmcnt(0)
	ds_read_b128 v[128:131], v140
	ds_read_b128 v[132:135], v140 offset:1024
	ds_read_b128 v[136:139], v140 offset:2048
	ds_read_b128 v[140:143], v140 offset:3072
	ds_read_b128 v[144:147], v156
	ds_read_b128 v[148:151], v156 offset:1024
	ds_read_b128 v[152:155], v156 offset:2048
	ds_read_b128 v[156:159], v156 offset:3072
	v_lshl_add_u64 v[192:193], s[12:13], 0, v[216:217]
	s_add_i32 m0, s20, 0xc000
	ds_read_b128 v[160:163], v246
	ds_read_b128 v[164:167], v246 offset:1024
	ds_read_b128 v[168:171], v246 offset:2048
	ds_read_b128 v[172:175], v246 offset:3072
	ds_read_b128 v[176:179], v246 offset:4096
	ds_read_b128 v[180:183], v246 offset:5120
	ds_read_b128 v[184:187], v246 offset:6144
	ds_read_b128 v[188:191], v246 offset:7168
	global_load_lds_dwordx4 v[192:193], off
	v_lshl_add_u64 v[192:193], s[12:13], 0, v[218:219]
	s_add_i32 m0, s20, 0xe000
	s_nop 0
	global_load_lds_dwordx4 v[192:193], off
	s_waitcnt vmcnt(8)
	s_waitcnt lgkmcnt(0)
	s_barrier
	s_waitcnt lgkmcnt(0)
	v_mfma_f32_16x16x32_bf16 v[124:127], v[128:131], v[160:163], v[124:127]
	v_mfma_f32_16x16x32_bf16 v[120:123], v[136:139], v[160:163], v[120:123]
	v_mfma_f32_16x16x32_bf16 v[116:119], v[128:131], v[168:171], v[116:119]
	v_mfma_f32_16x16x32_bf16 v[112:115], v[136:139], v[168:171], v[112:115]
	v_mfma_f32_16x16x32_bf16 v[100:103], v[128:131], v[176:179], v[100:103]
	v_mfma_f32_16x16x32_bf16 v[96:99], v[136:139], v[176:179], v[96:99]
	v_mfma_f32_16x16x32_bf16 v[84:87], v[128:131], v[184:187], v[84:87]
	v_mfma_f32_16x16x32_bf16 v[80:83], v[136:139], v[184:187], v[80:83]
	v_mfma_f32_16x16x32_bf16 v[124:127], v[132:135], v[164:167], v[124:127]
	v_mfma_f32_16x16x32_bf16 v[120:123], v[140:143], v[164:167], v[120:123]
	v_mfma_f32_16x16x32_bf16 v[116:119], v[132:135], v[172:175], v[116:119]
	v_mfma_f32_16x16x32_bf16 v[112:115], v[140:143], v[172:175], v[112:115]
	v_mfma_f32_16x16x32_bf16 v[100:103], v[132:135], v[180:183], v[100:103]
	v_mfma_f32_16x16x32_bf16 v[96:99], v[140:143], v[180:183], v[96:99]
	v_mfma_f32_16x16x32_bf16 v[84:87], v[132:135], v[188:191], v[84:87]
	v_mfma_f32_16x16x32_bf16 v[80:83], v[140:143], v[188:191], v[80:83]
	v_mfma_f32_16x16x32_bf16 v[108:111], v[144:147], v[160:163], v[108:111]
	v_mfma_f32_16x16x32_bf16 v[104:107], v[152:155], v[160:163], v[104:107]
	v_mfma_f32_16x16x32_bf16 v[92:95], v[144:147], v[168:171], v[92:95]
	v_mfma_f32_16x16x32_bf16 v[88:91], v[152:155], v[168:171], v[88:91]
	v_mfma_f32_16x16x32_bf16 v[76:79], v[144:147], v[176:179], v[76:79]
	v_mfma_f32_16x16x32_bf16 v[72:75], v[152:155], v[176:179], v[72:75]
	v_mfma_f32_16x16x32_bf16 v[68:71], v[144:147], v[184:187], v[68:71]
	v_mfma_f32_16x16x32_bf16 v[64:67], v[152:155], v[184:187], v[64:67]
	v_mfma_f32_16x16x32_bf16 v[108:111], v[148:151], v[164:167], v[108:111]
	v_mfma_f32_16x16x32_bf16 v[104:107], v[156:159], v[164:167], v[104:107]
	v_mfma_f32_16x16x32_bf16 v[92:95], v[148:151], v[172:175], v[92:95]
	v_mfma_f32_16x16x32_bf16 v[88:91], v[156:159], v[172:175], v[88:91]
	v_mfma_f32_16x16x32_bf16 v[76:79], v[148:151], v[180:183], v[76:79]
	v_mfma_f32_16x16x32_bf16 v[72:75], v[156:159], v[180:183], v[72:75]
	v_mfma_f32_16x16x32_bf16 v[68:71], v[148:151], v[188:191], v[68:71]
	v_mfma_f32_16x16x32_bf16 v[64:67], v[156:159], v[188:191], v[64:67]
	s_barrier
; #define PG8_STAGE(bufoff, gbase, voff) do { _Pragma("unroll") for (int _i = 0; _i < 2; ++_i) \
;         __builtin_amdgcn_global_load_lds((const unsigned*)((const char*)(gbase) + (voff)[_i]), (PG8_LAS unsigned*)(lds + (bufoff) + ldsw + _i * 8192), 16, 0, 0); } while (0)
; #define PG8_LDA(dst, b, h) do { _Pragma("unroll") for (int m = 0; m < 4; ++m) _Pragma("unroll") for (int k = 0; k < 2; ++k) dst[m][k] = *(const PG8_LAS bf16x8*)(lds + PG8_SA(b, h) + aoff + m * 2048 + k * 1024); } while (0)
; #define PG8_LDB(dst, b, h) do { _Pragma("unroll") for (int n = 0; n < 2; ++n) _Pragma("unroll") for (int k = 0; k < 2; ++k) dst[n][k] = *(const PG8_LAS bf16x8*)(lds + PG8_SB(b, h) + boff + n * 2048 + k * 1024); } while (0)
; #define PG8_MMA(ai, bj, At, Bt) do { __builtin_amdgcn_s_setprio(1); _Pragma("unroll") for (int m = 0; m < 4; ++m) _Pragma("unroll") for (int n = 0; n < 2; ++n) _Pragma("unroll") for (int k = 0; k < 2; ++k) \
;         acc[ai][bj][m][n] = __builtin_amdgcn_mfma_f32_16x16x32_bf16(Bt[n][k], At[m][k], acc[ai][bj][m][n], 0, 0, 0); __builtin_amdgcn_s_setprio(0); } while (0)
; #define PG8_WAIT_V(n) asm volatile("s_waitcnt vmcnt(" #n ")" ::: "memory")
; #define PG8_WAIT_L(n) asm volatile("s_waitcnt lgkmcnt(" #n ")" ::: "memory")
; #define PG8_BAR __builtin_amdgcn_s_barrier()
; #define PG8_SCHED __builtin_amdgcn_sched_barrier(0)
; template <class Epi, class Sched, bool ALIGN_EPI = false, bool SP2 = false>
; __device__ __forceinline__ void gemm_phase(PG8_LAS unsigned char* lds, const Gemm g, const Sched& S, const Epi& E) {
;     ...
;             PG8_WAIT_V(8); PG8_WAIT_L(0); PG8_BAR; PG8_MMA(0, 0, At, B0); PG8_MMA(0, 1, At, B1); PG8_BAR; PG8_SCHED;
;             PG8_LDA(At, 0, 1); PG8_STAGE(PG8_SB(0, 0), b2, voffB); PG8_STAGE(PG8_SB(0, 1), b2 + hstep, voffB); PG8_STAGE(PG8_SA(0, 0), a2, voffA);
;             PG8_WAIT_V(8); PG8_WAIT_L(0); PG8_BAR; PG8_MMA(1, 0, At, B0); PG8_MMA(1, 1, At, B1); PG8_BAR; PG8_SCHED;
;             PG8_LDB(B0, 1, 0); PG8_LDB(B1, 1, 1); PG8_SCHED; PG8_LDA(At, 1, 0); PG8_STAGE(PG8_SA(0, 1), a2 + hstep, voffA);
;             PG8_WAIT_V(8); PG8_WAIT_L(0); PG8_BAR; PG8_MMA(0, 0, At, B0); PG8_MMA(0, 1, At, B1); PG8_BAR; PG8_SCHED;
	s_add_i32 s33, s33, s91
	v_lshl_add_u64 v[192:193], s[2:3], 0, v[208:209]
	s_mov_b32 m0, s33
	ds_read_b128 v[160:163], v246 offset:16384
	ds_read_b128 v[164:167], v246 offset:17408
	ds_read_b128 v[168:171], v246 offset:18432
	ds_read_b128 v[172:175], v246 offset:19456
	ds_read_b128 v[176:179], v246 offset:20480
	ds_read_b128 v[180:183], v246 offset:21504
	ds_read_b128 v[184:187], v246 offset:22528
	ds_read_b128 v[188:191], v246 offset:23552
	global_load_lds_dwordx4 v[192:193], off
	s_add_i32 m0, s33, 0x2000
	v_lshl_add_u64 v[194:195], s[2:3], 0, v[214:215]
	s_add_u32 s2, s2, s86
	s_addc_u32 s3, s3, 0
	s_add_i32 s0, s0, s91
	global_load_lds_dwordx4 v[194:195], off
	v_lshl_add_u64 v[196:197], s[2:3], 0, v[208:209]
	s_mov_b32 m0, s0
	v_lshl_add_u64 v[198:199], s[2:3], 0, v[214:215]
	global_load_lds_dwordx4 v[196:197], off
	s_add_i32 m0, s0, 0x2000
	v_lshl_add_u64 v[200:201], s[14:15], 0, v[210:211]
	global_load_lds_dwordx4 v[198:199], off
	s_mov_b32 m0, s20
	v_lshl_add_u64 v[202:203], s[14:15], 0, v[212:213]
	global_load_lds_dwordx4 v[200:201], off
	s_mov_b32 m0, s99
	s_nop 0
	global_load_lds_dwordx4 v[202:203], off
	s_waitcnt vmcnt(8)
	s_waitcnt lgkmcnt(0)
	s_barrier
	s_waitcnt lgkmcnt(0)
	v_mfma_f32_16x16x32_bf16 v[60:63], v[128:131], v[160:163], v[60:63]
	v_mfma_f32_16x16x32_bf16 v[56:59], v[136:139], v[160:163], v[56:59]
	v_mfma_f32_16x16x32_bf16 v[52:55], v[128:131], v[168:171], v[52:55]
	v_mfma_f32_16x16x32_bf16 v[44:47], v[136:139], v[168:171], v[44:47]
	v_mfma_f32_16x16x32_bf16 v[36:39], v[128:131], v[176:179], v[36:39]
	v_mfma_f32_16x16x32_bf16 v[28:31], v[136:139], v[176:179], v[28:31]
	v_mfma_f32_16x16x32_bf16 v[20:23], v[128:131], v[184:187], v[20:23]
	v_mfma_f32_16x16x32_bf16 v[12:15], v[136:139], v[184:187], v[12:15]
	v_mfma_f32_16x16x32_bf16 v[60:63], v[132:135], v[164:167], v[60:63]
	v_mfma_f32_16x16x32_bf16 v[56:59], v[140:143], v[164:167], v[56:59]
	v_mfma_f32_16x16x32_bf16 v[52:55], v[132:135], v[172:175], v[52:55]
	v_mfma_f32_16x16x32_bf16 v[44:47], v[140:143], v[172:175], v[44:47]
	v_mfma_f32_16x16x32_bf16 v[36:39], v[132:135], v[180:183], v[36:39]
	v_mfma_f32_16x16x32_bf16 v[28:31], v[140:143], v[180:183], v[28:31]
	v_mfma_f32_16x16x32_bf16 v[20:23], v[132:135], v[188:191], v[20:23]
	v_mfma_f32_16x16x32_bf16 v[12:15], v[140:143], v[188:191], v[12:15]
	v_mfma_f32_16x16x32_bf16 v[48:51], v[144:147], v[160:163], v[48:51]
	v_mfma_f32_16x16x32_bf16 v[40:43], v[152:155], v[160:163], v[40:43]
	v_mfma_f32_16x16x32_bf16 v[32:35], v[144:147], v[168:171], v[32:35]
	v_mfma_f32_16x16x32_bf16 v[24:27], v[152:155], v[168:171], v[24:27]
	v_mfma_f32_16x16x32_bf16 v[16:19], v[144:147], v[176:179], v[16:19]
	v_mfma_f32_16x16x32_bf16 v[8:11], v[152:155], v[176:179], v[8:11]
	v_mfma_f32_16x16x32_bf16 v[4:7], v[144:147], v[184:187], v[4:7]
	v_mfma_f32_16x16x32_bf16 v[0:3], v[152:155], v[184:187], v[0:3]
	v_mfma_f32_16x16x32_bf16 v[48:51], v[148:151], v[164:167], v[48:51]
	v_mfma_f32_16x16x32_bf16 v[40:43], v[156:159], v[164:167], v[40:43]
	v_mfma_f32_16x16x32_bf16 v[32:35], v[148:151], v[172:175], v[32:35]
	v_mfma_f32_16x16x32_bf16 v[24:27], v[156:159], v[172:175], v[24:27]
	v_mfma_f32_16x16x32_bf16 v[16:19], v[148:151], v[180:183], v[16:19]
	v_mfma_f32_16x16x32_bf16 v[8:11], v[156:159], v[180:183], v[8:11]
	v_mfma_f32_16x16x32_bf16 v[4:7], v[148:151], v[188:191], v[4:7]
	v_mfma_f32_16x16x32_bf16 v[0:3], v[156:159], v[188:191], v[0:3]
	s_barrier
	s_add_i32 s0, 0, 0x18000
	s_add_i32 s33, 0, 0x1c000
	v_add_u32_e32 v140, s0, v252
	v_add_u32_e32 v156, s33, v252
	ds_read_b128 v[128:131], v140
	ds_read_b128 v[132:135], v140 offset:1024
	ds_read_b128 v[136:139], v140 offset:2048
	ds_read_b128 v[140:143], v140 offset:3072
	ds_read_b128 v[144:147], v156
	ds_read_b128 v[148:151], v156 offset:1024
	ds_read_b128 v[152:155], v156 offset:2048
	ds_read_b128 v[156:159], v156 offset:3072
	s_add_u32 s2, s14, s86
	s_addc_u32 s3, s15, 0
	s_mov_b32 m0, s39
	v_lshl_add_u64 v[204:205], s[2:3], 0, v[210:211]
	ds_read_b128 v[160:163], v246 offset:32768
	ds_read_b128 v[164:167], v246 offset:33792
	ds_read_b128 v[168:171], v246 offset:34816
	ds_read_b128 v[172:175], v246 offset:35840
	ds_read_b128 v[176:179], v246 offset:36864
	ds_read_b128 v[180:183], v246 offset:37888
	ds_read_b128 v[184:187], v246 offset:38912
	ds_read_b128 v[188:191], v246 offset:39936
	global_load_lds_dwordx4 v[204:205], off
	v_lshl_add_u64 v[204:205], s[2:3], 0, v[212:213]
	s_mov_b32 m0, s44
	s_nop 0
	global_load_lds_dwordx4 v[204:205], off
	s_waitcnt vmcnt(8)
	s_waitcnt lgkmcnt(0)
	s_barrier
; #define PG8_STAGE(bufoff, gbase, voff) do { _Pragma("unroll") for (int _i = 0; _i < 2; ++_i) \
;         __builtin_amdgcn_global_load_lds((const unsigned*)((const char*)(gbase) + (voff)[_i]), (PG8_LAS unsigned*)(lds + (bufoff) + ldsw + _i * 8192), 16, 0, 0); } while (0)
; #define PG8_LDA(dst, b, h) do { _Pragma("unroll") for (int m = 0; m < 4; ++m) _Pragma("unroll") for (int k = 0; k < 2; ++k) dst[m][k] = *(const PG8_LAS bf16x8*)(lds + PG8_SA(b, h) + aoff + m * 2048 + k * 1024); } while (0)
; #define PG8_MMA(ai, bj, At, Bt) do { __builtin_amdgcn_s_setprio(1); _Pragma("unroll") for (int m = 0; m < 4; ++m) _Pragma("unroll") for (int n = 0; n < 2; ++n) _Pragma("unroll") for (int k = 0; k < 2; ++k) \
;         acc[ai][bj][m][n] = __builtin_amdgcn_mfma_f32_16x16x32_bf16(Bt[n][k], At[m][k], acc[ai][bj][m][n], 0, 0, 0); __builtin_amdgcn_s_setprio(0); } while (0)
; #define PG8_WAIT_V(n) asm volatile("s_waitcnt vmcnt(" #n ")" ::: "memory")
; #define PG8_WAIT_L(n) asm volatile("s_waitcnt lgkmcnt(" #n ")" ::: "memory")
; #define PG8_BAR __builtin_amdgcn_s_barrier()
; #define PG8_SCHED __builtin_amdgcn_sched_barrier(0)
; template <class Epi, class Sched, bool ALIGN_EPI = false, bool SP2 = false>
; __device__ __forceinline__ void gemm_phase(PG8_LAS unsigned char* lds, const Gemm g, const Sched& S, const Epi& E) {
;     ...
;         for (int t = 0; t < nt; t += 2) {
;             const bool last = (t == nt - 2);
;     ...
;             PG8_WAIT_V(8); PG8_WAIT_L(0); PG8_BAR; PG8_MMA(0, 0, At, B0); PG8_MMA(0, 1, At, B1); PG8_BAR; PG8_SCHED;
;             PG8_LDA(At, 1, 1); PG8_STAGE(PG8_SB(1, 0), b3, voffB); PG8_STAGE(PG8_SB(1, 1), b3 + hstep, voffB); PG8_STAGE(PG8_SA(1, 0), a3, voffA);
;             PG8_WAIT_V(8); PG8_WAIT_L(0); PG8_BAR; PG8_MMA(1, 0, At, B0); PG8_MMA(1, 1, At, B1); PG8_BAR; PG8_SCHED;
;     ...
;         if constexpr (ALIGN_EPI) { if (wr == 0) PG8_BAR; }
	s_waitcnt lgkmcnt(0)
	v_mfma_f32_16x16x32_bf16 v[124:127], v[128:131], v[160:163], v[124:127]
	v_mfma_f32_16x16x32_bf16 v[120:123], v[136:139], v[160:163], v[120:123]
	v_mfma_f32_16x16x32_bf16 v[116:119], v[128:131], v[168:171], v[116:119]
	v_mfma_f32_16x16x32_bf16 v[112:115], v[136:139], v[168:171], v[112:115]
	v_mfma_f32_16x16x32_bf16 v[100:103], v[128:131], v[176:179], v[100:103]
	v_mfma_f32_16x16x32_bf16 v[96:99], v[136:139], v[176:179], v[96:99]
	v_mfma_f32_16x16x32_bf16 v[84:87], v[128:131], v[184:187], v[84:87]
	v_mfma_f32_16x16x32_bf16 v[80:83], v[136:139], v[184:187], v[80:83]
	v_mfma_f32_16x16x32_bf16 v[124:127], v[132:135], v[164:167], v[124:127]
	v_mfma_f32_16x16x32_bf16 v[120:123], v[140:143], v[164:167], v[120:123]
	v_mfma_f32_16x16x32_bf16 v[116:119], v[132:135], v[172:175], v[116:119]
	v_mfma_f32_16x16x32_bf16 v[112:115], v[140:143], v[172:175], v[112:115]
	v_mfma_f32_16x16x32_bf16 v[100:103], v[132:135], v[180:183], v[100:103]
	v_mfma_f32_16x16x32_bf16 v[96:99], v[140:143], v[180:183], v[96:99]
	v_mfma_f32_16x16x32_bf16 v[84:87], v[132:135], v[188:191], v[84:87]
	v_mfma_f32_16x16x32_bf16 v[80:83], v[140:143], v[188:191], v[80:83]
	v_mfma_f32_16x16x32_bf16 v[108:111], v[144:147], v[160:163], v[108:111]
	v_mfma_f32_16x16x32_bf16 v[104:107], v[152:155], v[160:163], v[104:107]
	v_mfma_f32_16x16x32_bf16 v[92:95], v[144:147], v[168:171], v[92:95]
	v_mfma_f32_16x16x32_bf16 v[88:91], v[152:155], v[168:171], v[88:91]
	v_mfma_f32_16x16x32_bf16 v[76:79], v[144:147], v[176:179], v[76:79]
	v_mfma_f32_16x16x32_bf16 v[72:75], v[152:155], v[176:179], v[72:75]
	v_mfma_f32_16x16x32_bf16 v[68:71], v[144:147], v[184:187], v[68:71]
	v_mfma_f32_16x16x32_bf16 v[64:67], v[152:155], v[184:187], v[64:67]
	v_mfma_f32_16x16x32_bf16 v[108:111], v[148:151], v[164:167], v[108:111]
	v_mfma_f32_16x16x32_bf16 v[104:107], v[156:159], v[164:167], v[104:107]
	v_mfma_f32_16x16x32_bf16 v[92:95], v[148:151], v[172:175], v[92:95]
	v_mfma_f32_16x16x32_bf16 v[88:91], v[156:159], v[172:175], v[88:91]
	v_mfma_f32_16x16x32_bf16 v[76:79], v[148:151], v[180:183], v[76:79]
	v_mfma_f32_16x16x32_bf16 v[72:75], v[156:159], v[180:183], v[72:75]
	v_mfma_f32_16x16x32_bf16 v[68:71], v[148:151], v[188:191], v[68:71]
	v_mfma_f32_16x16x32_bf16 v[64:67], v[156:159], v[188:191], v[64:67]
	s_barrier
	s_add_i32 s0, s0, s91
	v_lshl_add_u64 v[192:193], v[192:193], 0, s[66:67]
	s_mov_b32 m0, s0
	ds_read_b128 v[160:163], v246 offset:49152
	ds_read_b128 v[164:167], v246 offset:50176
	ds_read_b128 v[168:171], v246 offset:51200
	ds_read_b128 v[172:175], v246 offset:52224
	ds_read_b128 v[176:179], v246 offset:53248
	ds_read_b128 v[180:183], v246 offset:54272
	ds_read_b128 v[184:187], v246 offset:55296
	ds_read_b128 v[188:191], v246 offset:56320
	global_load_lds_dwordx4 v[192:193], off
	v_lshl_add_u64 v[192:193], v[194:195], 0, s[66:67]
	s_add_i32 m0, s0, 0x2000
	s_add_i32 s0, s33, s91
	global_load_lds_dwordx4 v[192:193], off
	v_lshl_add_u64 v[192:193], v[196:197], 0, s[66:67]
	s_mov_b32 m0, s0
	s_nop 0
	global_load_lds_dwordx4 v[192:193], off
	v_lshl_add_u64 v[192:193], v[198:199], 0, s[66:67]
	s_add_i32 m0, s0, 0x2000
	s_nop 0
	global_load_lds_dwordx4 v[192:193], off
	v_lshl_add_u64 v[192:193], v[200:201], 0, s[66:67]
	s_mov_b32 m0, s18
	s_nop 0
	global_load_lds_dwordx4 v[192:193], off
	v_lshl_add_u64 v[192:193], v[202:203], 0, s[66:67]
	s_mov_b32 m0, s19
	s_nop 0
	global_load_lds_dwordx4 v[192:193], off
	s_waitcnt vmcnt(8)
	s_waitcnt lgkmcnt(0)
	s_barrier
	s_waitcnt lgkmcnt(0)
	v_mfma_f32_16x16x32_bf16 v[60:63], v[128:131], v[160:163], v[60:63]
	v_mfma_f32_16x16x32_bf16 v[56:59], v[136:139], v[160:163], v[56:59]
	v_mfma_f32_16x16x32_bf16 v[52:55], v[128:131], v[168:171], v[52:55]
	v_mfma_f32_16x16x32_bf16 v[44:47], v[136:139], v[168:171], v[44:47]
	v_mfma_f32_16x16x32_bf16 v[36:39], v[128:131], v[176:179], v[36:39]
	v_mfma_f32_16x16x32_bf16 v[28:31], v[136:139], v[176:179], v[28:31]
	v_mfma_f32_16x16x32_bf16 v[20:23], v[128:131], v[184:187], v[20:23]
	v_mfma_f32_16x16x32_bf16 v[12:15], v[136:139], v[184:187], v[12:15]
	v_mfma_f32_16x16x32_bf16 v[60:63], v[132:135], v[164:167], v[60:63]
	v_mfma_f32_16x16x32_bf16 v[56:59], v[140:143], v[164:167], v[56:59]
	v_mfma_f32_16x16x32_bf16 v[52:55], v[132:135], v[172:175], v[52:55]
	v_mfma_f32_16x16x32_bf16 v[44:47], v[140:143], v[172:175], v[44:47]
	v_mfma_f32_16x16x32_bf16 v[36:39], v[132:135], v[180:183], v[36:39]
	v_mfma_f32_16x16x32_bf16 v[28:31], v[140:143], v[180:183], v[28:31]
	v_mfma_f32_16x16x32_bf16 v[20:23], v[132:135], v[188:191], v[20:23]
	v_mfma_f32_16x16x32_bf16 v[12:15], v[140:143], v[188:191], v[12:15]
	v_mfma_f32_16x16x32_bf16 v[48:51], v[144:147], v[160:163], v[48:51]
	v_mfma_f32_16x16x32_bf16 v[40:43], v[152:155], v[160:163], v[40:43]
	v_mfma_f32_16x16x32_bf16 v[32:35], v[144:147], v[168:171], v[32:35]
	v_mfma_f32_16x16x32_bf16 v[24:27], v[152:155], v[168:171], v[24:27]
	v_mfma_f32_16x16x32_bf16 v[16:19], v[144:147], v[176:179], v[16:19]
	v_mfma_f32_16x16x32_bf16 v[8:11], v[152:155], v[176:179], v[8:11]
	v_mfma_f32_16x16x32_bf16 v[4:7], v[144:147], v[184:187], v[4:7]
	v_mfma_f32_16x16x32_bf16 v[0:3], v[152:155], v[184:187], v[0:3]
	v_mfma_f32_16x16x32_bf16 v[48:51], v[148:151], v[164:167], v[48:51]
	v_mfma_f32_16x16x32_bf16 v[40:43], v[156:159], v[164:167], v[40:43]
	v_mfma_f32_16x16x32_bf16 v[32:35], v[148:151], v[172:175], v[32:35]
	v_mfma_f32_16x16x32_bf16 v[24:27], v[156:159], v[172:175], v[24:27]
	v_mfma_f32_16x16x32_bf16 v[16:19], v[148:151], v[180:183], v[16:19]
	v_mfma_f32_16x16x32_bf16 v[8:11], v[156:159], v[180:183], v[8:11]
	v_mfma_f32_16x16x32_bf16 v[4:7], v[148:151], v[188:191], v[4:7]
	v_mfma_f32_16x16x32_bf16 v[0:3], v[156:159], v[188:191], v[0:3]
	s_barrier
	s_add_u32 s12, s12, 0x100
	s_addc_u32 s13, s13, 0
	s_add_u32 s16, s16, 0x100
	s_addc_u32 s17, s17, 0
	s_cmp_ge_u32 s1, s45
	s_mov_b32 s0, s1
	s_cbranch_scc0 .LBB0_186
	s_and_b64 vcc, exec, s[92:93]
	s_cbranch_vccz .LBB0_189
	s_barrier
